# grid barrier: non-leader invalidate issued at arrival (only cache-bypassing polls happen between arrival and release), XCD leader publishes the generation before its own invalidate; on top of previous
# speedup vs baseline: 1.0092x; 1.0049x over previous
; __device__ __forceinline__ unsigned xb_ld(unsigned* p)              { return __hip_atomic_load(p, __ATOMIC_RELAXED, __HIP_MEMORY_SCOPE_AGENT); }
; __device__ __forceinline__ unsigned xb_add(unsigned* p, unsigned v) { return __hip_atomic_fetch_add(p, v, __ATOMIC_RELAXED, __HIP_MEMORY_SCOPE_AGENT); }
; #define XB_SPIN(cond, bar) do { unsigned _sp = 0; while (cond) { __builtin_amdgcn_s_sleep(1); \
;     if ((++_sp & 255u) == 0u) { if (xb_ld(&(bar)[XB_TMO])) break; if (_sp > XB_SPIN_CAP) { atomicAdd(&(bar)[XB_TMO], 1u); break; } } } } while (0)
; __device__ __forceinline__ void xcd_barrier(const XcdBarrier& b) {
;     ...
;         const unsigned old = xb_add(&bar[XB_XSUB(b.x)], 1u);
;         const unsigned gen = old / nloc;
;         if (old + 1u == (gen + 1u) * nloc) {
;             __builtin_amdgcn_fence(__ATOMIC_RELEASE, "agent");
;             asm volatile("s_waitcnt vmcnt(0)" ::: "memory");
;             const unsigned og = xb_add(&bar[XB_TOP], 1u);
;             const unsigned tg = og / nx;
;             if (og + 1u == (tg + 1u) * nx) xb_add(&bar[XB_TOPGEN], 1u);
;             else XB_SPIN(xb_ld(&bar[XB_TOPGEN]) == tg, bar);
;             __builtin_amdgcn_fence(__ATOMIC_ACQUIRE, "agent");
;             xb_add(&bar[XB_XGEN(b.x)], 1u);
;             asm volatile("s_waitcnt vmcnt(0)" ::: "memory");
;         } else {
;             XB_SPIN(xb_ld(&bar[XB_XGEN(b.x)]) == gen, bar);
;             __builtin_amdgcn_fence(__ATOMIC_ACQUIRE, "agent");
;             asm volatile("s_waitcnt vmcnt(0)" ::: "memory");
.LBB0_148:
	global_atomic_add v3, v[130:131], v176, off sc0
	v_cvt_f32_u32_e32 v1, v2
	v_sub_u32_e32 v4, 0, v2
	v_rcp_iflag_f32_e32 v1, v1
	s_nop 0
	v_mul_f32_e32 v1, 0x4f7ffffe, v1
	v_cvt_u32_f32_e32 v1, v1
	v_mul_lo_u32 v4, v4, v1
	v_mul_hi_u32 v4, v1, v4
	v_add_u32_e32 v1, v1, v4
	s_waitcnt vmcnt(0)
	v_mul_hi_u32 v1, v3, v1
	v_mul_lo_u32 v4, v1, v2
	v_sub_u32_e32 v4, v3, v4
	v_add_u32_e32 v5, 1, v1
	v_sub_u32_e32 v6, v4, v2
	v_cmp_ge_u32_e32 vcc, v4, v2
	v_add_u32_e32 v3, 1, v3
	s_nop 0
	v_cndmask_b32_e32 v1, v1, v5, vcc
	v_cndmask_b32_e32 v4, v4, v6, vcc
	v_add_u32_e32 v5, 1, v1
	v_cmp_ge_u32_e32 vcc, v4, v2
	s_nop 1
	v_cndmask_b32_e32 v1, v1, v5, vcc
	v_mul_lo_u32 v4, v2, v1
	v_add_u32_e32 v2, v4, v2
	v_cmp_ne_u32_e32 vcc, v3, v2
	s_and_saveexec_b64 s[6:7], vcc
	s_xor_b64 s[38:39], exec, s[6:7]
	s_cbranch_execz .LBB0_162
	s_waitcnt lgkmcnt(0)
	buffer_inv sc1
	global_load_dword v0, v[132:133], off sc1
	s_waitcnt vmcnt(0)
	v_cmp_eq_u32_e32 vcc, v0, v1
	s_and_saveexec_b64 s[40:41], vcc
	s_cbranch_execz .LBB0_161
	s_mov_b32 s2, 1
	s_mov_b64 s[42:43], 0
	s_branch .LBB0_152

; __device__ __forceinline__ unsigned xb_ld(unsigned* p)              { return __hip_atomic_load(p, __ATOMIC_RELAXED, __HIP_MEMORY_SCOPE_AGENT); }
; #define XB_SPIN(cond, bar) do { unsigned _sp = 0; while (cond) { __builtin_amdgcn_s_sleep(1); \
;     if ((++_sp & 255u) == 0u) { if (xb_ld(&(bar)[XB_TMO])) break; if (_sp > XB_SPIN_CAP) { atomicAdd(&(bar)[XB_TMO], 1u); break; } } } } while (0)
; __device__ __forceinline__ void xcd_barrier(const XcdBarrier& b) {
;     ...
;         } else {
;             XB_SPIN(xb_ld(&bar[XB_XGEN(b.x)]) == gen, bar);
;             __builtin_amdgcn_fence(__ATOMIC_ACQUIRE, "agent");
;             asm volatile("s_waitcnt vmcnt(0)" ::: "memory");
;         }
.LBB0_161:
	s_or_b64 exec, exec, s[40:41]
	s_waitcnt vmcnt(0)
	s_waitcnt vmcnt(0)

; __device__ __forceinline__ unsigned xb_ld(unsigned* p)              { return __hip_atomic_load(p, __ATOMIC_RELAXED, __HIP_MEMORY_SCOPE_AGENT); }
; __device__ __forceinline__ unsigned xb_add(unsigned* p, unsigned v) { return __hip_atomic_fetch_add(p, v, __ATOMIC_RELAXED, __HIP_MEMORY_SCOPE_AGENT); }
; #define XB_SPIN(cond, bar) do { unsigned _sp = 0; while (cond) { __builtin_amdgcn_s_sleep(1); \
;     if ((++_sp & 255u) == 0u) { if (xb_ld(&(bar)[XB_TMO])) break; if (_sp > XB_SPIN_CAP) { atomicAdd(&(bar)[XB_TMO], 1u); break; } } } } while (0)
; __device__ __forceinline__ void xcd_barrier(const XcdBarrier& b) {
;     ...
;         const unsigned old = xb_add(&bar[XB_XSUB(b.x)], 1u);
;         const unsigned gen = old / nloc;
;         if (old + 1u == (gen + 1u) * nloc) {
;             __builtin_amdgcn_fence(__ATOMIC_RELEASE, "agent");
;             asm volatile("s_waitcnt vmcnt(0)" ::: "memory");
;             const unsigned og = xb_add(&bar[XB_TOP], 1u);
;             const unsigned tg = og / nx;
;             if (og + 1u == (tg + 1u) * nx) xb_add(&bar[XB_TOPGEN], 1u);
;             else XB_SPIN(xb_ld(&bar[XB_TOPGEN]) == tg, bar);
;             __builtin_amdgcn_fence(__ATOMIC_ACQUIRE, "agent");
;             xb_add(&bar[XB_XGEN(b.x)], 1u);
;             asm volatile("s_waitcnt vmcnt(0)" ::: "memory");
;         } else {
;             XB_SPIN(xb_ld(&bar[XB_XGEN(b.x)]) == gen, bar);
;             __builtin_amdgcn_fence(__ATOMIC_ACQUIRE, "agent");
;             asm volatile("s_waitcnt vmcnt(0)" ::: "memory");
.LBB0_208:
	global_atomic_add v3, v[130:131], v176, off sc0
	v_cvt_f32_u32_e32 v1, v2
	v_sub_u32_e32 v4, 0, v2
	v_rcp_iflag_f32_e32 v1, v1
	s_nop 0
	v_mul_f32_e32 v1, 0x4f7ffffe, v1
	v_cvt_u32_f32_e32 v1, v1
	v_mul_lo_u32 v4, v4, v1
	v_mul_hi_u32 v4, v1, v4
	v_add_u32_e32 v1, v1, v4
	s_waitcnt vmcnt(0)
	v_mul_hi_u32 v1, v3, v1
	v_mul_lo_u32 v4, v1, v2
	v_sub_u32_e32 v4, v3, v4
	v_add_u32_e32 v5, 1, v1
	v_cmp_ge_u32_e32 vcc, v4, v2
	v_add_u32_e32 v3, 1, v3
	s_nop 0
	v_cndmask_b32_e32 v1, v1, v5, vcc
	v_sub_u32_e32 v5, v4, v2
	v_cndmask_b32_e32 v4, v4, v5, vcc
	v_add_u32_e32 v5, 1, v1
	v_cmp_ge_u32_e32 vcc, v4, v2
	s_nop 1
	v_cndmask_b32_e32 v1, v1, v5, vcc
	v_mul_lo_u32 v4, v2, v1
	v_add_u32_e32 v2, v4, v2
	v_cmp_ne_u32_e32 vcc, v3, v2
	s_and_saveexec_b64 s[6:7], vcc
	s_xor_b64 s[38:39], exec, s[6:7]
	s_cbranch_execz .LBB0_222
	s_waitcnt lgkmcnt(0)
	buffer_inv sc1
	global_load_dword v0, v[132:133], off sc1
	s_waitcnt vmcnt(0)
	v_cmp_eq_u32_e32 vcc, v0, v1
	s_and_saveexec_b64 s[40:41], vcc
	s_cbranch_execz .LBB0_221
	s_mov_b32 s2, 1
	s_mov_b64 s[42:43], 0
	s_branch .LBB0_212

; __device__ __forceinline__ unsigned xb_ld(unsigned* p)              { return __hip_atomic_load(p, __ATOMIC_RELAXED, __HIP_MEMORY_SCOPE_AGENT); }
; __device__ __forceinline__ unsigned xb_add(unsigned* p, unsigned v) { return __hip_atomic_fetch_add(p, v, __ATOMIC_RELAXED, __HIP_MEMORY_SCOPE_AGENT); }
; #define XB_SPIN(cond, bar) do { unsigned _sp = 0; while (cond) { __builtin_amdgcn_s_sleep(1); \
;     if ((++_sp & 255u) == 0u) { if (xb_ld(&(bar)[XB_TMO])) break; if (_sp > XB_SPIN_CAP) { atomicAdd(&(bar)[XB_TMO], 1u); break; } } } } while (0)
; __device__ __forceinline__ void xcd_barrier(const XcdBarrier& b) {
;     ...
;         const unsigned old = xb_add(&bar[XB_XSUB(b.x)], 1u);
;         const unsigned gen = old / nloc;
;         if (old + 1u == (gen + 1u) * nloc) {
;             __builtin_amdgcn_fence(__ATOMIC_RELEASE, "agent");
;             asm volatile("s_waitcnt vmcnt(0)" ::: "memory");
;             const unsigned og = xb_add(&bar[XB_TOP], 1u);
;             const unsigned tg = og / nx;
;             if (og + 1u == (tg + 1u) * nx) xb_add(&bar[XB_TOPGEN], 1u);
;             else XB_SPIN(xb_ld(&bar[XB_TOPGEN]) == tg, bar);
;             __builtin_amdgcn_fence(__ATOMIC_ACQUIRE, "agent");
;             xb_add(&bar[XB_XGEN(b.x)], 1u);
;             asm volatile("s_waitcnt vmcnt(0)" ::: "memory");
;         } else {
;             XB_SPIN(xb_ld(&bar[XB_XGEN(b.x)]) == gen, bar);
;             __builtin_amdgcn_fence(__ATOMIC_ACQUIRE, "agent");
;             asm volatile("s_waitcnt vmcnt(0)" ::: "memory");
.LBB0_536:
	global_atomic_add v3, v[130:131], v176, off sc0
	v_cvt_f32_u32_e32 v1, v2
	v_sub_u32_e32 v4, 0, v2
	v_rcp_iflag_f32_e32 v1, v1
	s_nop 0
	v_mul_f32_e32 v1, 0x4f7ffffe, v1
	v_cvt_u32_f32_e32 v1, v1
	v_mul_lo_u32 v4, v4, v1
	v_mul_hi_u32 v4, v1, v4
	v_add_u32_e32 v1, v1, v4
	s_waitcnt vmcnt(0)
	v_mul_hi_u32 v1, v3, v1
	v_mul_lo_u32 v4, v1, v2
	v_sub_u32_e32 v4, v3, v4
	v_add_u32_e32 v5, 1, v1
	v_cmp_ge_u32_e32 vcc, v4, v2
	v_add_u32_e32 v3, 1, v3
	s_nop 0
	v_cndmask_b32_e32 v1, v1, v5, vcc
	v_sub_u32_e32 v5, v4, v2
	v_cndmask_b32_e32 v4, v4, v5, vcc
	v_add_u32_e32 v5, 1, v1
	v_cmp_ge_u32_e32 vcc, v4, v2
	s_nop 1
	v_cndmask_b32_e32 v1, v1, v5, vcc
	v_mul_lo_u32 v4, v2, v1
	v_add_u32_e32 v2, v4, v2
	v_cmp_ne_u32_e32 vcc, v3, v2
	s_and_saveexec_b64 s[6:7], vcc
	s_xor_b64 s[38:39], exec, s[6:7]
	s_cbranch_execz .LBB0_550
	s_waitcnt lgkmcnt(0)
	buffer_inv sc1
	global_load_dword v0, v[132:133], off sc1
	s_waitcnt vmcnt(0)
	v_cmp_eq_u32_e32 vcc, v0, v1
	s_and_saveexec_b64 s[40:41], vcc
	s_cbranch_execz .LBB0_549
	s_mov_b32 s6, 1
	s_mov_b64 s[42:43], 0
	s_branch .LBB0_540
